# first phase seam uses the XCD-hierarchical grid barrier like every other seam instead of the cooperative-groups grid sync
# speedup vs baseline: 1.0081x; 1.0003x over previous
; DI void xcd_barrier(const XcdBarrier& b) {
;   asm volatile("s_waitcnt vmcnt(0)" ::: "memory");
;   __syncthreads();
;   if (threadIdx.x == 0) {
;     unsigned* bar = b.bar;
;     asm volatile("" : "+s"(bar));
;     __builtin_amdgcn_s_waitcnt(0);
;     unsigned nloc = b.st[0], nx = b.st[1];
;     if (nloc == 0u) { xcd_barrier_complete(bar, b.x, nloc, nx); b.st[0] = nloc; b.st[1] = nx; }
; __global__ void __launch_bounds__(512) mega_kernel(Params P) {
;     ...
;     if (ph + 1 < P.ph_hi) {
;       if (ph == P.ph_lo) cg::this_grid().sync();
;       else xcd_barrier(xb);
;     }
.LBB0_846:
	v_readlane_b32 s0, v253, 17
	v_readlane_b32 s1, v253, 18
	s_cmp_lg_u32 s2, s0
	s_mov_b64 s[0:1], -1
	s_nop 0
	s_waitcnt vmcnt(0)
	s_waitcnt vmcnt(0) lgkmcnt(0)
	s_barrier
	s_mov_b64 s[46:47], exec
	v_readlane_b32 s0, v253, 19
	v_readlane_b32 s1, v253, 20
	s_and_b64 s[0:1], s[46:47], s[0:1]
	s_mov_b64 exec, s[0:1]
	s_cbranch_execz .LBB0_891
	v_readlane_b32 s54, v253, 21
	s_add_i32 s24, 0, 0x24000
	v_readlane_b32 s55, v253, 22
	v_mov_b32_e32 v0, s24
	s_waitcnt vmcnt(0) expcnt(0) lgkmcnt(0)
	ds_read_b32 v2, v0
	v_readlane_b32 s0, v255, 23
	s_waitcnt lgkmcnt(0)
	v_cmp_ne_u32_e32 vcc, 0, v2
	v_mov_b32_e32 v0, s0
	ds_read_b32 v0, v0
	s_cbranch_vccnz .LBB0_862
	s_add_u32 s2, s54, 0x1000
	s_addc_u32 s3, s55, 0
	s_add_u32 s40, s54, 0x1100
	s_addc_u32 s41, s55, 0
	s_add_u32 s42, s54, 0x1200
	s_addc_u32 s43, s55, 0
	s_add_u32 s44, s54, 0x1300
	s_addc_u32 s45, s55, 0
	s_mov_b32 s25, 1
	s_mov_b64 s[50:51], 0
	s_branch .LBB0_852
